# norm2: NORMMOD row loop software-pipelined (next rows' x loads double-buffered, adaLN shift/scale kept in registers per slot, batched reductions)
# speedup vs baseline: 1.0016x; 1.0016x over previous
;   __host__ __device__ __forceinline__ float* ctxres() const { return (float*)(wsl() + OFF_CTXRES); }
; __device__ __forceinline__ int obid() { int t = blockIdx.x; asm volatile("" : "+s"(t)); return t; }
; __device__ __forceinline__ void normmod_phase(const Params& p, int layer, int which, int first) {
;     ...
;   const float* xlat = first ? p.x : p.out;
;   for (int row0 = obid() * 8 + w; row0 < NTOK; row0 += 2 * stride) {
;     float4 v[2][4];
;     bool ok[2];
; #pragma unroll
;     for (int q = 0; q < 2; ++q) {
;       int row = row0 + q * stride;
;       ok[q] = row < NTOK;
;       if (ok[q]) {
;         int b = row >= TPB ? 1 : 0, u = row - b * TPB;
;         const float* x = (u < CTX) ? p.ctxres() + (size_t)(b * CTX + u) * D : xlat + ((size_t)b * SEQ + (u - CTX)) * D;
; #pragma unroll
;         for (int i = 0; i < 4; ++i) v[q][i] = *(const float4*)(x + i * 256 + lane * 4);
;       }
;     }
;     ...
;         float4 g4 = *(const float4*)(g + cidx);
.LBB0_919:
	v_readfirstlane_b32 s60, v24
	v_lshlrev_b32_e32 v99, 2, v26
	s_lshl_b32 s62, s80, 3
	s_lshl_b32 s63, s80, 4
	global_load_dwordx4 v[178:181], v[28:29], off offset:0
	global_load_dwordx4 v[182:185], v[28:29], off offset:1024
	global_load_dwordx4 v[186:189], v[28:29], off offset:2048
	global_load_dwordx4 v[190:193], v[28:29], off offset:3072
	s_mov_b32 s64, -1
	s_mov_b32 s65, -1
	s_cmpk_gt_u32 s60, 0x20ff
	s_cselect_b32 s56, 1, 0
	s_mul_i32 s57, s56, 0x2100
	s_sub_i32 s57, s60, s57
	s_cmpk_lt_u32 s57, 0x100
	s_cbranch_scc0 .Lnm_latI
	s_lshl_b32 s58, s56, 8
	s_add_i32 s58, s58, s57
	s_mov_b32 s59, 0
	s_lshl_b64 s[58:59], s[58:59], 12
	s_add_u32 s70, s8, s58
	s_addc_u32 s71, s9, s59
	s_mov_b32 s56, 2
	s_branch .Lnm_mdI
.Lnm_latI:
	s_lshl_b32 s58, s56, 13
	s_add_i32 s58, s58, s57
	s_addk_i32 s58, 0xff00
	s_mov_b32 s59, 0
	s_lshl_b64 s[58:59], s[58:59], 12
	s_add_u32 s70, s6, s58
	s_addc_u32 s71, s7, s59
.Lnm_mdI:
	global_load_dwordx4 v[0:3], v99, s[70:71] offset:0
	global_load_dwordx4 v[4:7], v99, s[70:71] offset:1024
	global_load_dwordx4 v[8:11], v99, s[70:71] offset:2048
	global_load_dwordx4 v[12:15], v99, s[70:71] offset:3072
	s_add_i32 s61, s60, s62
	s_cmpk_lt_u32 s61, 0x4200
	s_cbranch_scc0 .Lnm_pro1
	s_cmpk_gt_u32 s61, 0x20ff
	s_cselect_b32 s56, 1, 0
	s_mul_i32 s57, s56, 0x2100
	s_sub_i32 s57, s61, s57
	s_cmpk_lt_u32 s57, 0x100
	s_cbranch_scc0 .Lnm_latJ
	s_lshl_b32 s58, s56, 8
	s_add_i32 s58, s58, s57
	s_mov_b32 s59, 0
	s_lshl_b64 s[58:59], s[58:59], 12
	s_add_u32 s72, s8, s58
	s_addc_u32 s73, s9, s59
	s_mov_b32 s56, 2
	s_branch .Lnm_mdJ
.Lnm_latJ:
	s_lshl_b32 s58, s56, 13
	s_add_i32 s58, s58, s57
	s_addk_i32 s58, 0xff00
	s_mov_b32 s59, 0
	s_lshl_b64 s[58:59], s[58:59], 12
	s_add_u32 s72, s6, s58
	s_addc_u32 s73, s7, s59
.Lnm_mdJ:
	global_load_dwordx4 v[200:203], v99, s[72:73] offset:0
	global_load_dwordx4 v[204:207], v99, s[72:73] offset:1024
	global_load_dwordx4 v[208:211], v99, s[72:73] offset:2048
	global_load_dwordx4 v[212:215], v99, s[72:73] offset:3072

;   __host__ __device__ __forceinline__ float* ctxres() const { return (float*)(wsl() + OFF_CTXRES); }
; __device__ __forceinline__ void normmod_phase(const Params& p, int layer, int which, int first) {
;     ...
;       int row = row0 + q * stride;
;       ok[q] = row < NTOK;
;       if (ok[q]) {
;         int b = row >= TPB ? 1 : 0, u = row - b * TPB;
;         const float* x = (u < CTX) ? p.ctxres() + (size_t)(b * CTX + u) * D : xlat + ((size_t)b * SEQ + (u - CTX)) * D;
.Lnm_it0:
	s_add_i32 s61, s60, s62
	s_mov_b32 s66, 0
	s_cmpk_gt_u32 s60, 0x20ff
	s_cselect_b32 s56, 1, 0
	s_mul_i32 s57, s56, 0x2100
	s_sub_i32 s57, s60, s57
	s_cmpk_lt_u32 s57, 0x100
	s_cbranch_scc0 .Lnm_latA0
	s_lshl_b32 s58, s56, 8
	s_add_i32 s58, s58, s57
	s_mov_b32 s59, 0
	s_lshl_b64 s[58:59], s[58:59], 12
	s_add_u32 s40, s8, s58
	s_addc_u32 s41, s9, s59
	s_mov_b32 s56, 2
	s_branch .Lnm_mdA0

;   __host__ __device__ __forceinline__ float* mod() const { return (float*)(wsl() + OFF_MOD); }
; __device__ __forceinline__ void normmod_phase(const Params& p, int layer, int which, int first) {
;     ...
;       const float* md = p.mod() + ((size_t)layer * 3 + condof(row)) * NMOD + which * 3 * D;
;     ...
;         float4 g4 = *(const float4*)(g + cidx);
;         float4 sh = *(const float4*)(md + cidx);
;         float4 sc = *(const float4*)(md + D + cidx);
.Lnm_mdA0:
	s_mov_b32 s74, s56
	s_add_i32 s56, s56, s18
	s_mul_i32 s56, s56, 0x9000
	s_add_u32 s42, s10, s56
	s_addc_u32 s43, s11, 0
	s_add_u32 s44, s42, 0x1000
	s_addc_u32 s45, s43, 0
	s_mov_b32 s52, s60
	s_mov_b32 s53, 0
	s_lshl_b64 s[52:53], s[52:53], 11
	s_cmp_eq_u32 s74, s64
	s_cbranch_scc1 .Lnm_okA0
	global_load_dwordx4 v[100:103], v99, s[42:43] offset:0
	global_load_dwordx4 v[104:107], v99, s[42:43] offset:1024
	global_load_dwordx4 v[108:111], v99, s[42:43] offset:2048
	global_load_dwordx4 v[112:115], v99, s[42:43] offset:3072
	global_load_dwordx4 v[116:119], v99, s[44:45] offset:0
	global_load_dwordx4 v[120:123], v99, s[44:45] offset:1024
	global_load_dwordx4 v[124:127], v99, s[44:45] offset:2048
	global_load_dwordx4 v[128:131], v99, s[44:45] offset:3072
	s_mov_b32 s64, s74
	s_mov_b32 s66, 1
.Lnm_okA0:
	s_cmpk_lt_u32 s61, 0x4200
	s_cbranch_scc0 .Lnm_onlyA0
	s_cmpk_gt_u32 s61, 0x20ff
	s_cselect_b32 s56, 1, 0
	s_mul_i32 s57, s56, 0x2100
	s_sub_i32 s57, s61, s57
	s_cmpk_lt_u32 s57, 0x100
	s_cbranch_scc0 .Lnm_latB0
	s_lshl_b32 s58, s56, 8
	s_add_i32 s58, s58, s57
	s_mov_b32 s59, 0
	s_lshl_b64 s[58:59], s[58:59], 12
	s_add_u32 s46, s8, s58
	s_addc_u32 s47, s9, s59
	s_mov_b32 s56, 2
	s_branch .Lnm_mdB0

;   __host__ __device__ __forceinline__ float* ctxres() const { return (float*)(wsl() + OFF_CTXRES); }
;   __host__ __device__ __forceinline__ float* mod() const { return (float*)(wsl() + OFF_MOD); }
; __device__ __forceinline__ void normmod_phase(const Params& p, int layer, int which, int first) {
;     ...
;     for (int q = 0; q < 2; ++q) {
;       int row = row0 + q * stride;
;       ok[q] = row < NTOK;
;       if (ok[q]) {
;         int b = row >= TPB ? 1 : 0, u = row - b * TPB;
;         const float* x = (u < CTX) ? p.ctxres() + (size_t)(b * CTX + u) * D : xlat + ((size_t)b * SEQ + (u - CTX)) * D;
; #pragma unroll
;         for (int i = 0; i < 4; ++i) v[q][i] = *(const float4*)(x + i * 256 + lane * 4);
;     ...
;       const float* md = p.mod() + ((size_t)layer * 3 + condof(row)) * NMOD + which * 3 * D;
;     ...
;         float4 g4 = *(const float4*)(g + cidx);
;         float4 sh = *(const float4*)(md + cidx);
;         float4 sc = *(const float4*)(md + D + cidx);
.Lnm_mdB0:
	s_mov_b32 s75, s56
	s_add_i32 s56, s56, s18
	s_mul_i32 s56, s56, 0x9000
	s_add_u32 s48, s10, s56
	s_addc_u32 s49, s11, 0
	s_add_u32 s50, s48, 0x1000
	s_addc_u32 s51, s49, 0
	s_mov_b32 s54, s61
	s_mov_b32 s55, 0
	s_lshl_b64 s[54:55], s[54:55], 11
	s_cmp_eq_u32 s75, s65
	s_cbranch_scc1 .Lnm_okB0
	global_load_dwordx4 v[132:135], v99, s[48:49] offset:0
	global_load_dwordx4 v[136:139], v99, s[48:49] offset:1024
	global_load_dwordx4 v[140:143], v99, s[48:49] offset:2048
	global_load_dwordx4 v[144:147], v99, s[48:49] offset:3072
	global_load_dwordx4 v[148:151], v99, s[50:51] offset:0
	global_load_dwordx4 v[152:155], v99, s[50:51] offset:1024
	global_load_dwordx4 v[156:159], v99, s[50:51] offset:2048
	global_load_dwordx4 v[160:163], v99, s[50:51] offset:3072
	s_mov_b32 s65, s75
	s_mov_b32 s66, 1
.Lnm_okB0:
	s_add_i32 s67, s60, s63
	s_cmpk_lt_u32 s67, 0x4200
	s_cbranch_scc0 .Lnm_nopf0
	s_cmpk_gt_u32 s67, 0x20ff
	s_cselect_b32 s56, 1, 0
	s_mul_i32 s57, s56, 0x2100
	s_sub_i32 s57, s67, s57
	s_cmpk_lt_u32 s57, 0x100
	s_cbranch_scc0 .Lnm_latP0
	s_lshl_b32 s58, s56, 8
	s_add_i32 s58, s58, s57
	s_mov_b32 s59, 0
	s_lshl_b64 s[58:59], s[58:59], 12
	s_add_u32 s70, s8, s58
	s_addc_u32 s71, s9, s59
	s_mov_b32 s56, 2
	s_branch .Lnm_mdP0

;   __host__ __device__ __forceinline__ float* ctxres() const { return (float*)(wsl() + OFF_CTXRES); }
; __device__ __forceinline__ void normmod_phase(const Params& p, int layer, int which, int first) {
;     ...
;     for (int q = 0; q < 2; ++q) {
;       int row = row0 + q * stride;
;       ok[q] = row < NTOK;
;       if (ok[q]) {
;         int b = row >= TPB ? 1 : 0, u = row - b * TPB;
;         const float* x = (u < CTX) ? p.ctxres() + (size_t)(b * CTX + u) * D : xlat + ((size_t)b * SEQ + (u - CTX)) * D;
; #pragma unroll
;         for (int i = 0; i < 4; ++i) v[q][i] = *(const float4*)(x + i * 256 + lane * 4);
.Lnm_mdP0:
	global_load_dwordx4 v[70:73], v99, s[70:71] offset:0
	global_load_dwordx4 v[74:77], v99, s[70:71] offset:1024
	global_load_dwordx4 v[78:81], v99, s[70:71] offset:2048
	global_load_dwordx4 v[82:85], v99, s[70:71] offset:3072
	s_add_i32 s68, s67, s62
	s_cmpk_lt_u32 s68, 0x4200
	s_cbranch_scc0 .Lnm_nopf0
	s_cmpk_gt_u32 s68, 0x20ff
	s_cselect_b32 s56, 1, 0
	s_mul_i32 s57, s56, 0x2100
	s_sub_i32 s57, s68, s57
	s_cmpk_lt_u32 s57, 0x100
	s_cbranch_scc0 .Lnm_latQ0
	s_lshl_b32 s58, s56, 8
	s_add_i32 s58, s58, s57
	s_mov_b32 s59, 0
	s_lshl_b64 s[58:59], s[58:59], 12
	s_add_u32 s72, s8, s58
	s_addc_u32 s73, s9, s59
	s_mov_b32 s56, 2
	s_branch .Lnm_mdQ0

; __device__ __forceinline__ void normmod_phase(const Params& p, int layer, int which, int first) {
;     ...
;       float ss = 0;
; #pragma unroll
;       for (int i = 0; i < 4; ++i) ss += v[q][i].x * v[q][i].x + v[q][i].y * v[q][i].y + v[q][i].z * v[q][i].z + v[q][i].w * v[q][i].w;
;       ss = wave_sum(ss);
.Lnm_mdQ0:
	global_load_dwordx4 v[236:239], v99, s[72:73] offset:0
	global_load_dwordx4 v[240:243], v99, s[72:73] offset:1024
	global_load_dwordx4 v[244:247], v99, s[72:73] offset:2048
	global_load_dwordx4 v[248:251], v99, s[72:73] offset:3072
.Lnm_nopf0:
	s_cmp_eq_u32 s66, 0
	s_cbranch_scc1 .Lnm_go0
	s_waitcnt vmcnt(0)
.Lnm_go0:
	v_mul_f32_e32 v40, v0, v0
	v_fmac_f32_e32 v40, v1, v1
	v_fmac_f32_e32 v40, v2, v2
	v_fmac_f32_e32 v40, v3, v3
	v_fmac_f32_e32 v40, v4, v4
	v_fmac_f32_e32 v40, v5, v5
	v_fmac_f32_e32 v40, v6, v6
	v_fmac_f32_e32 v40, v7, v7
	v_fmac_f32_e32 v40, v8, v8
	v_fmac_f32_e32 v40, v9, v9
	v_fmac_f32_e32 v40, v10, v10
	v_fmac_f32_e32 v40, v11, v11
	v_fmac_f32_e32 v40, v12, v12
	v_fmac_f32_e32 v40, v13, v13
	v_fmac_f32_e32 v40, v14, v14
	v_fmac_f32_e32 v40, v15, v15
	v_mul_f32_e32 v46, v200, v200
	v_fmac_f32_e32 v46, v201, v201
	v_fmac_f32_e32 v46, v202, v202
	v_fmac_f32_e32 v46, v203, v203
	v_fmac_f32_e32 v46, v204, v204
	v_fmac_f32_e32 v46, v205, v205
	v_fmac_f32_e32 v46, v206, v206
	v_fmac_f32_e32 v46, v207, v207
	v_fmac_f32_e32 v46, v208, v208
	v_fmac_f32_e32 v46, v209, v209
	v_fmac_f32_e32 v46, v210, v210
	v_fmac_f32_e32 v46, v211, v211
	v_fmac_f32_e32 v46, v212, v212
	v_fmac_f32_e32 v46, v213, v213
	v_fmac_f32_e32 v46, v214, v214
	v_fmac_f32_e32 v46, v215, v215
	ds_bpermute_b32 v41, v27, v40
	ds_bpermute_b32 v47, v27, v46
	s_waitcnt lgkmcnt(0)
	v_add_f32_e32 v40, v40, v41
	v_add_f32_e32 v46, v46, v47
	ds_bpermute_b32 v41, v31, v40
	ds_bpermute_b32 v47, v31, v46
	s_waitcnt lgkmcnt(0)
	v_add_f32_e32 v40, v40, v41
	v_add_f32_e32 v46, v46, v47
	ds_bpermute_b32 v41, v33, v40
	ds_bpermute_b32 v47, v33, v46
	s_waitcnt lgkmcnt(0)
	v_add_f32_e32 v40, v40, v41
	v_add_f32_e32 v46, v46, v47
	ds_bpermute_b32 v41, v35, v40
	ds_bpermute_b32 v47, v35, v46
	s_waitcnt lgkmcnt(0)
	v_add_f32_e32 v40, v40, v41
	v_add_f32_e32 v46, v46, v47
	ds_bpermute_b32 v41, v68, v40
	ds_bpermute_b32 v47, v68, v46
	s_waitcnt lgkmcnt(0)
	v_add_f32_e32 v40, v40, v41
	v_add_f32_e32 v46, v46, v47
	ds_bpermute_b32 v41, v69, v40
	ds_bpermute_b32 v47, v69, v46
	s_waitcnt lgkmcnt(0)
;   __host__ __device__ __forceinline__ bf16_t* H() const { return (bf16_t*)(wsl() + OFF_H); }
; __device__ __forceinline__ uint32_t pack2(float a, float b) { uint32_t r; asm("v_cvt_pk_bf16_f32 %0, %1, %2" : "=v"(r) : "v"(a), "v"(b)); return r; }
; __device__ __forceinline__ void normmod_phase(const Params& p, int layer, int which, int first) {
;     ...
;       float rstd = rsqrtf(ss * (1.0f / D) + 1e-6f);
; #pragma unroll
;       for (int i = 0; i < 4; ++i) {
;         int cidx = i * 256 + lane * 4;
;         float4 g4 = *(const float4*)(g + cidx);
;         float4 sh = *(const float4*)(md + cidx);
;         float4 sc = *(const float4*)(md + D + cidx);
;         float h0 = v[q][i].x * rstd * g4.x * (1.0f + sc.x) + sh.x;
;         float h1 = v[q][i].y * rstd * g4.y * (1.0f + sc.y) + sh.y;
;         float h2 = v[q][i].z * rstd * g4.z * (1.0f + sc.z) + sh.z;
;         float h3 = v[q][i].w * rstd * g4.w * (1.0f + sc.w) + sh.w;
;         uint2 o; o.x = pack2(h0, h1); o.y = pack2(h2, h3);
;         *(uint2*)(p.H() + (size_t)row * D + cidx) = o;
;       }
	v_add_f32_e32 v40, v40, v41
	v_add_f32_e32 v46, v46, v47
	v_fmamk_f32 v40, v40, 0x3a800000, v168
	s_mov_b32 s56, 0x800000
	v_mul_f32_e32 v41, 0x4b800000, v40
	v_cmp_gt_f32_e64 s[58:59], s56, v40
	s_nop 1
	v_cndmask_b32_e64 v40, v40, v41, s[58:59]
	v_rsq_f32_e32 v40, v40
	s_nop 0
	v_mul_f32_e32 v41, 0x45800000, v40
	v_cndmask_b32_e64 v40, v40, v41, s[58:59]
	v_lshl_add_u64 v[62:63], v[36:37], 0, s[52:53]
	v_mul_f32_e32 v0, v0, v40
	v_mul_f32_e32 v0, v178, v0
	v_add_f32_e32 v42, 1.0, v116
	v_mul_f32_e32 v1, v1, v40
	v_mul_f32_e32 v1, v179, v1
	v_add_f32_e32 v43, 1.0, v117
	v_mul_f32_e32 v2, v2, v40
	v_mul_f32_e32 v2, v180, v2
	v_add_f32_e32 v44, 1.0, v118
	v_mul_f32_e32 v3, v3, v40
	v_mul_f32_e32 v3, v181, v3
	v_add_f32_e32 v45, 1.0, v119
	v_fma_f32 v0, v42, v0, v100
	v_fma_f32 v1, v43, v1, v101
	v_fma_f32 v2, v44, v2, v102
	v_fma_f32 v3, v45, v3, v103
	v_cvt_pk_bf16_f32 v0, v0, v1
	v_cvt_pk_bf16_f32 v1, v2, v3
	global_store_dwordx2 v[62:63], v[0:1], off offset:0
	v_mul_f32_e32 v4, v4, v40
	v_mul_f32_e32 v4, v182, v4
	v_add_f32_e32 v42, 1.0, v120
	v_mul_f32_e32 v5, v5, v40
	v_mul_f32_e32 v5, v183, v5
	v_add_f32_e32 v43, 1.0, v121
	v_mul_f32_e32 v6, v6, v40
	v_mul_f32_e32 v6, v184, v6
	v_add_f32_e32 v44, 1.0, v122
	v_mul_f32_e32 v7, v7, v40
	v_mul_f32_e32 v7, v185, v7
	v_add_f32_e32 v45, 1.0, v123
	v_fma_f32 v4, v42, v4, v104
	v_fma_f32 v5, v43, v5, v105
	v_fma_f32 v6, v44, v6, v106
	v_fma_f32 v7, v45, v7, v107
	v_cvt_pk_bf16_f32 v4, v4, v5
	v_cvt_pk_bf16_f32 v5, v6, v7
	global_store_dwordx2 v[62:63], v[4:5], off offset:512
	v_mul_f32_e32 v8, v8, v40
	v_mul_f32_e32 v8, v186, v8
	v_add_f32_e32 v42, 1.0, v124
	v_mul_f32_e32 v9, v9, v40
	v_mul_f32_e32 v9, v187, v9
	v_add_f32_e32 v43, 1.0, v125
	v_mul_f32_e32 v10, v10, v40
	v_mul_f32_e32 v10, v188, v10
	v_add_f32_e32 v44, 1.0, v126
	v_mul_f32_e32 v11, v11, v40
	v_mul_f32_e32 v11, v189, v11
	v_add_f32_e32 v45, 1.0, v127
	v_fma_f32 v8, v42, v8, v108
	v_fma_f32 v9, v43, v9, v109
	v_fma_f32 v10, v44, v10, v110
	v_fma_f32 v11, v45, v11, v111
	v_cvt_pk_bf16_f32 v8, v8, v9
	v_cvt_pk_bf16_f32 v9, v10, v11
	global_store_dwordx2 v[62:63], v[8:9], off offset:1024
	v_mul_f32_e32 v12, v12, v40
	v_mul_f32_e32 v12, v190, v12
	v_add_f32_e32 v42, 1.0, v128
	v_mul_f32_e32 v13, v13, v40
	v_mul_f32_e32 v13, v191, v13
	v_add_f32_e32 v43, 1.0, v129
	v_mul_f32_e32 v14, v14, v40
	v_mul_f32_e32 v14, v192, v14
	v_add_f32_e32 v44, 1.0, v130
	v_mul_f32_e32 v15, v15, v40
	v_mul_f32_e32 v15, v193, v15
	v_add_f32_e32 v45, 1.0, v131
	v_fma_f32 v12, v42, v12, v112
	v_fma_f32 v13, v43, v13, v113
	v_fma_f32 v14, v44, v14, v114
	v_fma_f32 v15, v45, v15, v115
	v_cvt_pk_bf16_f32 v12, v12, v13
	v_cvt_pk_bf16_f32 v13, v14, v15
	global_store_dwordx2 v[62:63], v[12:13], off offset:1536
	v_fmamk_f32 v46, v46, 0x3a800000, v168
	s_mov_b32 s56, 0x800000
	v_mul_f32_e32 v47, 0x4b800000, v46
	v_cmp_gt_f32_e64 s[58:59], s56, v46
	s_nop 1
	v_cndmask_b32_e64 v46, v46, v47, s[58:59]
	v_rsq_f32_e32 v46, v46
	s_nop 0
	v_mul_f32_e32 v47, 0x45800000, v46
	v_cndmask_b32_e64 v46, v46, v47, s[58:59]
	v_lshl_add_u64 v[62:63], v[36:37], 0, s[54:55]
	v_mul_f32_e32 v200, v200, v46
	v_mul_f32_e32 v200, v178, v200
	v_add_f32_e32 v42, 1.0, v148
	v_mul_f32_e32 v201, v201, v46
	v_mul_f32_e32 v201, v179, v201
	v_add_f32_e32 v43, 1.0, v149
	v_mul_f32_e32 v202, v202, v46
	v_mul_f32_e32 v202, v180, v202
	v_add_f32_e32 v44, 1.0, v150
	v_mul_f32_e32 v203, v203, v46
	v_mul_f32_e32 v203, v181, v203
	v_add_f32_e32 v45, 1.0, v151
	v_fma_f32 v200, v42, v200, v132
	v_fma_f32 v201, v43, v201, v133
	v_fma_f32 v202, v44, v202, v134
	v_fma_f32 v203, v45, v203, v135
	v_cvt_pk_bf16_f32 v200, v200, v201
	v_cvt_pk_bf16_f32 v201, v202, v203
	global_store_dwordx2 v[62:63], v[200:201], off offset:0
	v_mul_f32_e32 v204, v204, v46
	v_mul_f32_e32 v204, v182, v204
	v_add_f32_e32 v42, 1.0, v152
	v_mul_f32_e32 v205, v205, v46
	v_mul_f32_e32 v205, v183, v205
	v_add_f32_e32 v43, 1.0, v153
	v_mul_f32_e32 v206, v206, v46
	v_mul_f32_e32 v206, v184, v206
	v_add_f32_e32 v44, 1.0, v154
	v_mul_f32_e32 v207, v207, v46
	v_mul_f32_e32 v207, v185, v207
	v_add_f32_e32 v45, 1.0, v155
	v_fma_f32 v204, v42, v204, v136
	v_fma_f32 v205, v43, v205, v137
	v_fma_f32 v206, v44, v206, v138
	v_fma_f32 v207, v45, v207, v139
	v_cvt_pk_bf16_f32 v204, v204, v205
	v_cvt_pk_bf16_f32 v205, v206, v207
	global_store_dwordx2 v[62:63], v[204:205], off offset:512
	v_mul_f32_e32 v208, v208, v46
	v_mul_f32_e32 v208, v186, v208
	v_add_f32_e32 v42, 1.0, v156
	v_mul_f32_e32 v209, v209, v46
	v_mul_f32_e32 v209, v187, v209
	v_add_f32_e32 v43, 1.0, v157
	v_mul_f32_e32 v210, v210, v46
	v_mul_f32_e32 v210, v188, v210
	v_add_f32_e32 v44, 1.0, v158
	v_mul_f32_e32 v211, v211, v46
	v_mul_f32_e32 v211, v189, v211
	v_add_f32_e32 v45, 1.0, v159
	v_fma_f32 v208, v42, v208, v140
	v_fma_f32 v209, v43, v209, v141
	v_fma_f32 v210, v44, v210, v142
	v_fma_f32 v211, v45, v211, v143
	v_cvt_pk_bf16_f32 v208, v208, v209
	v_cvt_pk_bf16_f32 v209, v210, v211
	global_store_dwordx2 v[62:63], v[208:209], off offset:1024
	v_mul_f32_e32 v212, v212, v46
	v_mul_f32_e32 v212, v190, v212
	v_add_f32_e32 v42, 1.0, v160
	v_mul_f32_e32 v213, v213, v46
	v_mul_f32_e32 v213, v191, v213
	v_add_f32_e32 v43, 1.0, v161
	v_mul_f32_e32 v214, v214, v46
	v_mul_f32_e32 v214, v192, v214
	v_add_f32_e32 v44, 1.0, v162
	v_mul_f32_e32 v215, v215, v46
	v_mul_f32_e32 v215, v193, v215
	v_add_f32_e32 v45, 1.0, v163
	v_fma_f32 v212, v42, v212, v144
	v_fma_f32 v213, v43, v213, v145
	v_fma_f32 v214, v44, v214, v146
	v_fma_f32 v215, v45, v215, v147
	v_cvt_pk_bf16_f32 v212, v212, v213
	v_cvt_pk_bf16_f32 v213, v214, v215
	global_store_dwordx2 v[62:63], v[212:213], off offset:1536
	s_waitcnt vmcnt(8)
	s_mov_b32 s60, s67
	s_branch .Lnm_adv0

;   __host__ __device__ __forceinline__ bf16_t* H() const { return (bf16_t*)(wsl() + OFF_H); }
; __device__ __forceinline__ uint32_t pack2(float a, float b) { uint32_t r; asm("v_cvt_pk_bf16_f32 %0, %1, %2" : "=v"(r) : "v"(a), "v"(b)); return r; }
; __device__ __forceinline__ void normmod_phase(const Params& p, int layer, int which, int first) {
;     ...
;       float ss = 0;
; #pragma unroll
;       for (int i = 0; i < 4; ++i) ss += v[q][i].x * v[q][i].x + v[q][i].y * v[q][i].y + v[q][i].z * v[q][i].z + v[q][i].w * v[q][i].w;
;       ss = wave_sum(ss);
;       float rstd = rsqrtf(ss * (1.0f / D) + 1e-6f);
; #pragma unroll
;       for (int i = 0; i < 4; ++i) {
;         int cidx = i * 256 + lane * 4;
;         float4 g4 = *(const float4*)(g + cidx);
;         float4 sh = *(const float4*)(md + cidx);
;         float4 sc = *(const float4*)(md + D + cidx);
;         float h0 = v[q][i].x * rstd * g4.x * (1.0f + sc.x) + sh.x;
;         float h1 = v[q][i].y * rstd * g4.y * (1.0f + sc.y) + sh.y;
;         float h2 = v[q][i].z * rstd * g4.z * (1.0f + sc.z) + sh.z;
;         float h3 = v[q][i].w * rstd * g4.w * (1.0f + sc.w) + sh.w;
;         uint2 o; o.x = pack2(h0, h1); o.y = pack2(h2, h3);
;         *(uint2*)(p.H() + (size_t)row * D + cidx) = o;
;       }
.Lnm_goA0:
	v_mul_f32_e32 v40, v0, v0
	v_fmac_f32_e32 v40, v1, v1
	v_fmac_f32_e32 v40, v2, v2
	v_fmac_f32_e32 v40, v3, v3
	v_fmac_f32_e32 v40, v4, v4
	v_fmac_f32_e32 v40, v5, v5
	v_fmac_f32_e32 v40, v6, v6
	v_fmac_f32_e32 v40, v7, v7
	v_fmac_f32_e32 v40, v8, v8
	v_fmac_f32_e32 v40, v9, v9
	v_fmac_f32_e32 v40, v10, v10
	v_fmac_f32_e32 v40, v11, v11
	v_fmac_f32_e32 v40, v12, v12
	v_fmac_f32_e32 v40, v13, v13
	v_fmac_f32_e32 v40, v14, v14
	v_fmac_f32_e32 v40, v15, v15
	ds_bpermute_b32 v41, v27, v40
	s_waitcnt lgkmcnt(0)
	v_add_f32_e32 v40, v40, v41
	ds_bpermute_b32 v41, v31, v40
	s_waitcnt lgkmcnt(0)
	v_add_f32_e32 v40, v40, v41
	ds_bpermute_b32 v41, v33, v40
	s_waitcnt lgkmcnt(0)
	v_add_f32_e32 v40, v40, v41
	ds_bpermute_b32 v41, v35, v40
	s_waitcnt lgkmcnt(0)
	v_add_f32_e32 v40, v40, v41
	ds_bpermute_b32 v41, v68, v40
	s_waitcnt lgkmcnt(0)
	v_add_f32_e32 v40, v40, v41
	ds_bpermute_b32 v41, v69, v40
	s_waitcnt lgkmcnt(0)
	v_add_f32_e32 v40, v40, v41
	v_fmamk_f32 v40, v40, 0x3a800000, v168
	s_mov_b32 s56, 0x800000
	v_mul_f32_e32 v41, 0x4b800000, v40
	v_cmp_gt_f32_e64 s[58:59], s56, v40
	s_nop 1
	v_cndmask_b32_e64 v40, v40, v41, s[58:59]
	v_rsq_f32_e32 v40, v40
	s_nop 0
	v_mul_f32_e32 v41, 0x45800000, v40
	v_cndmask_b32_e64 v40, v40, v41, s[58:59]
	v_lshl_add_u64 v[62:63], v[36:37], 0, s[52:53]
	v_mul_f32_e32 v0, v0, v40
	v_mul_f32_e32 v0, v178, v0
	v_add_f32_e32 v42, 1.0, v116
	v_mul_f32_e32 v1, v1, v40
	v_mul_f32_e32 v1, v179, v1
	v_add_f32_e32 v43, 1.0, v117
	v_mul_f32_e32 v2, v2, v40
	v_mul_f32_e32 v2, v180, v2
	v_add_f32_e32 v44, 1.0, v118
	v_mul_f32_e32 v3, v3, v40
	v_mul_f32_e32 v3, v181, v3
	v_add_f32_e32 v45, 1.0, v119
	v_fma_f32 v0, v42, v0, v100
	v_fma_f32 v1, v43, v1, v101
	v_fma_f32 v2, v44, v2, v102
	v_fma_f32 v3, v45, v3, v103
	v_cvt_pk_bf16_f32 v0, v0, v1
	v_cvt_pk_bf16_f32 v1, v2, v3
	global_store_dwordx2 v[62:63], v[0:1], off offset:0
	v_mul_f32_e32 v4, v4, v40
	v_mul_f32_e32 v4, v182, v4
	v_add_f32_e32 v42, 1.0, v120
	v_mul_f32_e32 v5, v5, v40
	v_mul_f32_e32 v5, v183, v5
	v_add_f32_e32 v43, 1.0, v121
	v_mul_f32_e32 v6, v6, v40
	v_mul_f32_e32 v6, v184, v6
	v_add_f32_e32 v44, 1.0, v122
	v_mul_f32_e32 v7, v7, v40
	v_mul_f32_e32 v7, v185, v7
	v_add_f32_e32 v45, 1.0, v123
	v_fma_f32 v4, v42, v4, v104
	v_fma_f32 v5, v43, v5, v105
	v_fma_f32 v6, v44, v6, v106
	v_fma_f32 v7, v45, v7, v107
	v_cvt_pk_bf16_f32 v4, v4, v5
	v_cvt_pk_bf16_f32 v5, v6, v7
	global_store_dwordx2 v[62:63], v[4:5], off offset:512
	v_mul_f32_e32 v8, v8, v40
	v_mul_f32_e32 v8, v186, v8
	v_add_f32_e32 v42, 1.0, v124
	v_mul_f32_e32 v9, v9, v40
	v_mul_f32_e32 v9, v187, v9
	v_add_f32_e32 v43, 1.0, v125
	v_mul_f32_e32 v10, v10, v40
	v_mul_f32_e32 v10, v188, v10
	v_add_f32_e32 v44, 1.0, v126
	v_mul_f32_e32 v11, v11, v40
	v_mul_f32_e32 v11, v189, v11
	v_add_f32_e32 v45, 1.0, v127
	v_fma_f32 v8, v42, v8, v108
	v_fma_f32 v9, v43, v9, v109
	v_fma_f32 v10, v44, v10, v110
	v_fma_f32 v11, v45, v11, v111
	v_cvt_pk_bf16_f32 v8, v8, v9
	v_cvt_pk_bf16_f32 v9, v10, v11
	global_store_dwordx2 v[62:63], v[8:9], off offset:1024
	v_mul_f32_e32 v12, v12, v40
	v_mul_f32_e32 v12, v190, v12
	v_add_f32_e32 v42, 1.0, v128
	v_mul_f32_e32 v13, v13, v40
	v_mul_f32_e32 v13, v191, v13
	v_add_f32_e32 v43, 1.0, v129
	v_mul_f32_e32 v14, v14, v40
	v_mul_f32_e32 v14, v192, v14
	v_add_f32_e32 v44, 1.0, v130
	v_mul_f32_e32 v15, v15, v40
	v_mul_f32_e32 v15, v193, v15
	v_add_f32_e32 v45, 1.0, v131
	v_fma_f32 v12, v42, v12, v112
	v_fma_f32 v13, v43, v13, v113
	v_fma_f32 v14, v44, v14, v114
	v_fma_f32 v15, v45, v15, v115
	v_cvt_pk_bf16_f32 v12, v12, v13
	v_cvt_pk_bf16_f32 v13, v14, v15
	global_store_dwordx2 v[62:63], v[12:13], off offset:1536
	s_movk_i32 s60, 0x4200
.Lnm_adv0:
	s_cmpk_lt_u32 s60, 0x4200
	s_cbranch_scc1 .Lnm_it1
	s_branch .Lnm_done

;   __host__ __device__ __forceinline__ float* ctxres() const { return (float*)(wsl() + OFF_CTXRES); }
; __device__ __forceinline__ void normmod_phase(const Params& p, int layer, int which, int first) {
;     ...
;     for (int q = 0; q < 2; ++q) {
;       int row = row0 + q * stride;
;       ok[q] = row < NTOK;
;       if (ok[q]) {
;         int b = row >= TPB ? 1 : 0, u = row - b * TPB;
;         const float* x = (u < CTX) ? p.ctxres() + (size_t)(b * CTX + u) * D : xlat + ((size_t)b * SEQ + (u - CTX)) * D;
; #pragma unroll
;         for (int i = 0; i < 4; ++i) v[q][i] = *(const float4*)(x + i * 256 + lane * 4);
.Lnm_mdP1:
	global_load_dwordx4 v[0:3], v99, s[70:71] offset:0
	global_load_dwordx4 v[4:7], v99, s[70:71] offset:1024
	global_load_dwordx4 v[8:11], v99, s[70:71] offset:2048
	global_load_dwordx4 v[12:15], v99, s[70:71] offset:3072
	s_add_i32 s68, s67, s62
	s_cmpk_lt_u32 s68, 0x4200
	s_cbranch_scc0 .Lnm_nopf1
	s_cmpk_gt_u32 s68, 0x20ff
	s_cselect_b32 s56, 1, 0
	s_mul_i32 s57, s56, 0x2100
	s_sub_i32 s57, s68, s57
	s_cmpk_lt_u32 s57, 0x100
	s_cbranch_scc0 .Lnm_latQ1
	s_lshl_b32 s58, s56, 8
	s_add_i32 s58, s58, s57
	s_mov_b32 s59, 0
	s_lshl_b64 s[58:59], s[58:59], 12
	s_add_u32 s72, s8, s58
	s_addc_u32 s73, s9, s59
	s_mov_b32 s56, 2
	s_branch .Lnm_mdQ1

; __device__ __forceinline__ void normmod_phase(const Params& p, int layer, int which, int first) {
;     ...
;       float ss = 0;
; #pragma unroll
;       for (int i = 0; i < 4; ++i) ss += v[q][i].x * v[q][i].x + v[q][i].y * v[q][i].y + v[q][i].z * v[q][i].z + v[q][i].w * v[q][i].w;
;       ss = wave_sum(ss);
.Lnm_go1:
	v_mul_f32_e32 v40, v70, v70
	v_fmac_f32_e32 v40, v71, v71
	v_fmac_f32_e32 v40, v72, v72
	v_fmac_f32_e32 v40, v73, v73
	v_fmac_f32_e32 v40, v74, v74
	v_fmac_f32_e32 v40, v75, v75
	v_fmac_f32_e32 v40, v76, v76
	v_fmac_f32_e32 v40, v77, v77
	v_fmac_f32_e32 v40, v78, v78
	v_fmac_f32_e32 v40, v79, v79
	v_fmac_f32_e32 v40, v80, v80
	v_fmac_f32_e32 v40, v81, v81
	v_fmac_f32_e32 v40, v82, v82
	v_fmac_f32_e32 v40, v83, v83
	v_fmac_f32_e32 v40, v84, v84
	v_fmac_f32_e32 v40, v85, v85
	v_mul_f32_e32 v46, v236, v236
	v_fmac_f32_e32 v46, v237, v237
	v_fmac_f32_e32 v46, v238, v238
	v_fmac_f32_e32 v46, v239, v239
	v_fmac_f32_e32 v46, v240, v240
	v_fmac_f32_e32 v46, v241, v241
	v_fmac_f32_e32 v46, v242, v242
	v_fmac_f32_e32 v46, v243, v243
	v_fmac_f32_e32 v46, v244, v244
	v_fmac_f32_e32 v46, v245, v245
	v_fmac_f32_e32 v46, v246, v246
	v_fmac_f32_e32 v46, v247, v247
	v_fmac_f32_e32 v46, v248, v248
	v_fmac_f32_e32 v46, v249, v249
	v_fmac_f32_e32 v46, v250, v250
	v_fmac_f32_e32 v46, v251, v251
	ds_bpermute_b32 v41, v27, v40
	ds_bpermute_b32 v47, v27, v46
	s_waitcnt lgkmcnt(0)
	v_add_f32_e32 v40, v40, v41
	v_add_f32_e32 v46, v46, v47
	ds_bpermute_b32 v41, v31, v40
	ds_bpermute_b32 v47, v31, v46
	s_waitcnt lgkmcnt(0)
	v_add_f32_e32 v40, v40, v41
	v_add_f32_e32 v46, v46, v47
	ds_bpermute_b32 v41, v33, v40
	ds_bpermute_b32 v47, v33, v46
	s_waitcnt lgkmcnt(0)
	v_add_f32_e32 v40, v40, v41
	v_add_f32_e32 v46, v46, v47
	ds_bpermute_b32 v41, v35, v40
	ds_bpermute_b32 v47, v35, v46
	s_waitcnt lgkmcnt(0)
	v_add_f32_e32 v40, v40, v41
	v_add_f32_e32 v46, v46, v47
	ds_bpermute_b32 v41, v68, v40
	ds_bpermute_b32 v47, v68, v46
	s_waitcnt lgkmcnt(0)
	v_add_f32_e32 v40, v40, v41
	v_add_f32_e32 v46, v46, v47
	ds_bpermute_b32 v41, v69, v40
	ds_bpermute_b32 v47, v69, v46
	s_waitcnt lgkmcnt(0)
;   __host__ __device__ __forceinline__ bf16_t* H() const { return (bf16_t*)(wsl() + OFF_H); }
; __device__ __forceinline__ uint32_t pack2(float a, float b) { uint32_t r; asm("v_cvt_pk_bf16_f32 %0, %1, %2" : "=v"(r) : "v"(a), "v"(b)); return r; }
; __device__ __forceinline__ void normmod_phase(const Params& p, int layer, int which, int first) {
;     ...
;       float rstd = rsqrtf(ss * (1.0f / D) + 1e-6f);
; #pragma unroll
;       for (int i = 0; i < 4; ++i) {
;         int cidx = i * 256 + lane * 4;
;         float4 g4 = *(const float4*)(g + cidx);
;         float4 sh = *(const float4*)(md + cidx);
;         float4 sc = *(const float4*)(md + D + cidx);
;         float h0 = v[q][i].x * rstd * g4.x * (1.0f + sc.x) + sh.x;
;         float h1 = v[q][i].y * rstd * g4.y * (1.0f + sc.y) + sh.y;
;         float h2 = v[q][i].z * rstd * g4.z * (1.0f + sc.z) + sh.z;
;         float h3 = v[q][i].w * rstd * g4.w * (1.0f + sc.w) + sh.w;
;         uint2 o; o.x = pack2(h0, h1); o.y = pack2(h2, h3);
;         *(uint2*)(p.H() + (size_t)row * D + cidx) = o;
;       }
	v_add_f32_e32 v40, v40, v41
	v_add_f32_e32 v46, v46, v47
	v_fmamk_f32 v40, v40, 0x3a800000, v168
	s_mov_b32 s56, 0x800000
	v_mul_f32_e32 v41, 0x4b800000, v40
	v_cmp_gt_f32_e64 s[58:59], s56, v40
	s_nop 1
	v_cndmask_b32_e64 v40, v40, v41, s[58:59]
	v_rsq_f32_e32 v40, v40
	s_nop 0
	v_mul_f32_e32 v41, 0x45800000, v40
	v_cndmask_b32_e64 v40, v40, v41, s[58:59]
	v_lshl_add_u64 v[62:63], v[36:37], 0, s[52:53]
	v_mul_f32_e32 v70, v70, v40
	v_mul_f32_e32 v70, v178, v70
	v_add_f32_e32 v42, 1.0, v116
	v_mul_f32_e32 v71, v71, v40
	v_mul_f32_e32 v71, v179, v71
	v_add_f32_e32 v43, 1.0, v117
	v_mul_f32_e32 v72, v72, v40
	v_mul_f32_e32 v72, v180, v72
	v_add_f32_e32 v44, 1.0, v118
	v_mul_f32_e32 v73, v73, v40
	v_mul_f32_e32 v73, v181, v73
	v_add_f32_e32 v45, 1.0, v119
	v_fma_f32 v70, v42, v70, v100
	v_fma_f32 v71, v43, v71, v101
	v_fma_f32 v72, v44, v72, v102
	v_fma_f32 v73, v45, v73, v103
	v_cvt_pk_bf16_f32 v70, v70, v71
	v_cvt_pk_bf16_f32 v71, v72, v73
	global_store_dwordx2 v[62:63], v[70:71], off offset:0
	v_mul_f32_e32 v74, v74, v40
	v_mul_f32_e32 v74, v182, v74
	v_add_f32_e32 v42, 1.0, v120
	v_mul_f32_e32 v75, v75, v40
	v_mul_f32_e32 v75, v183, v75
	v_add_f32_e32 v43, 1.0, v121
	v_mul_f32_e32 v76, v76, v40
	v_mul_f32_e32 v76, v184, v76
	v_add_f32_e32 v44, 1.0, v122
	v_mul_f32_e32 v77, v77, v40
	v_mul_f32_e32 v77, v185, v77
	v_add_f32_e32 v45, 1.0, v123
	v_fma_f32 v74, v42, v74, v104
	v_fma_f32 v75, v43, v75, v105
	v_fma_f32 v76, v44, v76, v106
	v_fma_f32 v77, v45, v77, v107
	v_cvt_pk_bf16_f32 v74, v74, v75
	v_cvt_pk_bf16_f32 v75, v76, v77
	global_store_dwordx2 v[62:63], v[74:75], off offset:512
	v_mul_f32_e32 v78, v78, v40
	v_mul_f32_e32 v78, v186, v78
	v_add_f32_e32 v42, 1.0, v124
	v_mul_f32_e32 v79, v79, v40
	v_mul_f32_e32 v79, v187, v79
	v_add_f32_e32 v43, 1.0, v125
	v_mul_f32_e32 v80, v80, v40
	v_mul_f32_e32 v80, v188, v80
	v_add_f32_e32 v44, 1.0, v126
	v_mul_f32_e32 v81, v81, v40
	v_mul_f32_e32 v81, v189, v81
	v_add_f32_e32 v45, 1.0, v127
	v_fma_f32 v78, v42, v78, v108
	v_fma_f32 v79, v43, v79, v109
	v_fma_f32 v80, v44, v80, v110
	v_fma_f32 v81, v45, v81, v111
	v_cvt_pk_bf16_f32 v78, v78, v79
	v_cvt_pk_bf16_f32 v79, v80, v81
	global_store_dwordx2 v[62:63], v[78:79], off offset:1024
	v_mul_f32_e32 v82, v82, v40
	v_mul_f32_e32 v82, v190, v82
	v_add_f32_e32 v42, 1.0, v128
	v_mul_f32_e32 v83, v83, v40
	v_mul_f32_e32 v83, v191, v83
	v_add_f32_e32 v43, 1.0, v129
	v_mul_f32_e32 v84, v84, v40
	v_mul_f32_e32 v84, v192, v84
	v_add_f32_e32 v44, 1.0, v130
	v_mul_f32_e32 v85, v85, v40
	v_mul_f32_e32 v85, v193, v85
	v_add_f32_e32 v45, 1.0, v131
	v_fma_f32 v82, v42, v82, v112
	v_fma_f32 v83, v43, v83, v113
	v_fma_f32 v84, v44, v84, v114
	v_fma_f32 v85, v45, v85, v115
	v_cvt_pk_bf16_f32 v82, v82, v83
	v_cvt_pk_bf16_f32 v83, v84, v85
	global_store_dwordx2 v[62:63], v[82:83], off offset:1536
	v_fmamk_f32 v46, v46, 0x3a800000, v168
	s_mov_b32 s56, 0x800000
	v_mul_f32_e32 v47, 0x4b800000, v46
	v_cmp_gt_f32_e64 s[58:59], s56, v46
	s_nop 1
	v_cndmask_b32_e64 v46, v46, v47, s[58:59]
	v_rsq_f32_e32 v46, v46
	s_nop 0
	v_mul_f32_e32 v47, 0x45800000, v46
	v_cndmask_b32_e64 v46, v46, v47, s[58:59]
	v_lshl_add_u64 v[62:63], v[36:37], 0, s[54:55]
	v_mul_f32_e32 v236, v236, v46
	v_mul_f32_e32 v236, v178, v236
	v_add_f32_e32 v42, 1.0, v148
	v_mul_f32_e32 v237, v237, v46
	v_mul_f32_e32 v237, v179, v237
	v_add_f32_e32 v43, 1.0, v149
	v_mul_f32_e32 v238, v238, v46
	v_mul_f32_e32 v238, v180, v238
	v_add_f32_e32 v44, 1.0, v150
	v_mul_f32_e32 v239, v239, v46
	v_mul_f32_e32 v239, v181, v239
	v_add_f32_e32 v45, 1.0, v151
	v_fma_f32 v236, v42, v236, v132
	v_fma_f32 v237, v43, v237, v133
	v_fma_f32 v238, v44, v238, v134
	v_fma_f32 v239, v45, v239, v135
	v_cvt_pk_bf16_f32 v236, v236, v237
	v_cvt_pk_bf16_f32 v237, v238, v239
	global_store_dwordx2 v[62:63], v[236:237], off offset:0
	v_mul_f32_e32 v240, v240, v46
	v_mul_f32_e32 v240, v182, v240
	v_add_f32_e32 v42, 1.0, v152
	v_mul_f32_e32 v241, v241, v46
	v_mul_f32_e32 v241, v183, v241
	v_add_f32_e32 v43, 1.0, v153
	v_mul_f32_e32 v242, v242, v46
	v_mul_f32_e32 v242, v184, v242
	v_add_f32_e32 v44, 1.0, v154
	v_mul_f32_e32 v243, v243, v46
	v_mul_f32_e32 v243, v185, v243
	v_add_f32_e32 v45, 1.0, v155
	v_fma_f32 v240, v42, v240, v136
	v_fma_f32 v241, v43, v241, v137
	v_fma_f32 v242, v44, v242, v138
	v_fma_f32 v243, v45, v243, v139
	v_cvt_pk_bf16_f32 v240, v240, v241
	v_cvt_pk_bf16_f32 v241, v242, v243
	global_store_dwordx2 v[62:63], v[240:241], off offset:512
	v_mul_f32_e32 v244, v244, v46
	v_mul_f32_e32 v244, v186, v244
	v_add_f32_e32 v42, 1.0, v156
	v_mul_f32_e32 v245, v245, v46
	v_mul_f32_e32 v245, v187, v245
	v_add_f32_e32 v43, 1.0, v157
	v_mul_f32_e32 v246, v246, v46
	v_mul_f32_e32 v246, v188, v246
	v_add_f32_e32 v44, 1.0, v158
	v_mul_f32_e32 v247, v247, v46
	v_mul_f32_e32 v247, v189, v247
	v_add_f32_e32 v45, 1.0, v159
	v_fma_f32 v244, v42, v244, v140
	v_fma_f32 v245, v43, v245, v141
	v_fma_f32 v246, v44, v246, v142
	v_fma_f32 v247, v45, v247, v143
	v_cvt_pk_bf16_f32 v244, v244, v245
	v_cvt_pk_bf16_f32 v245, v246, v247
	global_store_dwordx2 v[62:63], v[244:245], off offset:1024
	v_mul_f32_e32 v248, v248, v46
	v_mul_f32_e32 v248, v190, v248
	v_add_f32_e32 v42, 1.0, v160
	v_mul_f32_e32 v249, v249, v46
	v_mul_f32_e32 v249, v191, v249
	v_add_f32_e32 v43, 1.0, v161
	v_mul_f32_e32 v250, v250, v46
	v_mul_f32_e32 v250, v192, v250
	v_add_f32_e32 v44, 1.0, v162
	v_mul_f32_e32 v251, v251, v46
	v_mul_f32_e32 v251, v193, v251
	v_add_f32_e32 v45, 1.0, v163
	v_fma_f32 v248, v42, v248, v144
	v_fma_f32 v249, v43, v249, v145
	v_fma_f32 v250, v44, v250, v146
	v_fma_f32 v251, v45, v251, v147
	v_cvt_pk_bf16_f32 v248, v248, v249
	v_cvt_pk_bf16_f32 v249, v250, v251
	global_store_dwordx2 v[62:63], v[248:249], off offset:1536
	s_waitcnt vmcnt(8)
	s_mov_b32 s60, s67
	s_branch .Lnm_adv1

;   __host__ __device__ __forceinline__ bf16_t* H() const { return (bf16_t*)(wsl() + OFF_H); }
; __device__ __forceinline__ uint32_t pack2(float a, float b) { uint32_t r; asm("v_cvt_pk_bf16_f32 %0, %1, %2" : "=v"(r) : "v"(a), "v"(b)); return r; }
; __device__ __forceinline__ void normmod_phase(const Params& p, int layer, int which, int first) {
;     ...
;       float ss = 0;
; #pragma unroll
;       for (int i = 0; i < 4; ++i) ss += v[q][i].x * v[q][i].x + v[q][i].y * v[q][i].y + v[q][i].z * v[q][i].z + v[q][i].w * v[q][i].w;
;       ss = wave_sum(ss);
;       float rstd = rsqrtf(ss * (1.0f / D) + 1e-6f);
; #pragma unroll
;       for (int i = 0; i < 4; ++i) {
;         int cidx = i * 256 + lane * 4;
;         float4 g4 = *(const float4*)(g + cidx);
;         float4 sh = *(const float4*)(md + cidx);
;         float4 sc = *(const float4*)(md + D + cidx);
;         float h0 = v[q][i].x * rstd * g4.x * (1.0f + sc.x) + sh.x;
;         float h1 = v[q][i].y * rstd * g4.y * (1.0f + sc.y) + sh.y;
;         float h2 = v[q][i].z * rstd * g4.z * (1.0f + sc.z) + sh.z;
;         float h3 = v[q][i].w * rstd * g4.w * (1.0f + sc.w) + sh.w;
;         uint2 o; o.x = pack2(h0, h1); o.y = pack2(h2, h3);
;         *(uint2*)(p.H() + (size_t)row * D + cidx) = o;
;       }
;     }
;   }
; }
.Lnm_goA1:
	v_mul_f32_e32 v40, v70, v70
	v_fmac_f32_e32 v40, v71, v71
	v_fmac_f32_e32 v40, v72, v72
	v_fmac_f32_e32 v40, v73, v73
	v_fmac_f32_e32 v40, v74, v74
	v_fmac_f32_e32 v40, v75, v75
	v_fmac_f32_e32 v40, v76, v76
	v_fmac_f32_e32 v40, v77, v77
	v_fmac_f32_e32 v40, v78, v78
	v_fmac_f32_e32 v40, v79, v79
	v_fmac_f32_e32 v40, v80, v80
	v_fmac_f32_e32 v40, v81, v81
	v_fmac_f32_e32 v40, v82, v82
	v_fmac_f32_e32 v40, v83, v83
	v_fmac_f32_e32 v40, v84, v84
	v_fmac_f32_e32 v40, v85, v85
	ds_bpermute_b32 v41, v27, v40
	s_waitcnt lgkmcnt(0)
	v_add_f32_e32 v40, v40, v41
	ds_bpermute_b32 v41, v31, v40
	s_waitcnt lgkmcnt(0)
	v_add_f32_e32 v40, v40, v41
	ds_bpermute_b32 v41, v33, v40
	s_waitcnt lgkmcnt(0)
	v_add_f32_e32 v40, v40, v41
	ds_bpermute_b32 v41, v35, v40
	s_waitcnt lgkmcnt(0)
	v_add_f32_e32 v40, v40, v41
	ds_bpermute_b32 v41, v68, v40
	s_waitcnt lgkmcnt(0)
	v_add_f32_e32 v40, v40, v41
	ds_bpermute_b32 v41, v69, v40
	s_waitcnt lgkmcnt(0)
	v_add_f32_e32 v40, v40, v41
	v_fmamk_f32 v40, v40, 0x3a800000, v168
	s_mov_b32 s56, 0x800000
	v_mul_f32_e32 v41, 0x4b800000, v40
	v_cmp_gt_f32_e64 s[58:59], s56, v40
	s_nop 1
	v_cndmask_b32_e64 v40, v40, v41, s[58:59]
	v_rsq_f32_e32 v40, v40
	s_nop 0
	v_mul_f32_e32 v41, 0x45800000, v40
	v_cndmask_b32_e64 v40, v40, v41, s[58:59]
	v_lshl_add_u64 v[62:63], v[36:37], 0, s[52:53]
	v_mul_f32_e32 v70, v70, v40
	v_mul_f32_e32 v70, v178, v70
	v_add_f32_e32 v42, 1.0, v116
	v_mul_f32_e32 v71, v71, v40
	v_mul_f32_e32 v71, v179, v71
	v_add_f32_e32 v43, 1.0, v117
	v_mul_f32_e32 v72, v72, v40
	v_mul_f32_e32 v72, v180, v72
	v_add_f32_e32 v44, 1.0, v118
	v_mul_f32_e32 v73, v73, v40
	v_mul_f32_e32 v73, v181, v73
	v_add_f32_e32 v45, 1.0, v119
	v_fma_f32 v70, v42, v70, v100
	v_fma_f32 v71, v43, v71, v101
	v_fma_f32 v72, v44, v72, v102
	v_fma_f32 v73, v45, v73, v103
	v_cvt_pk_bf16_f32 v70, v70, v71
	v_cvt_pk_bf16_f32 v71, v72, v73
	global_store_dwordx2 v[62:63], v[70:71], off offset:0
	v_mul_f32_e32 v74, v74, v40
	v_mul_f32_e32 v74, v182, v74
	v_add_f32_e32 v42, 1.0, v120
	v_mul_f32_e32 v75, v75, v40
	v_mul_f32_e32 v75, v183, v75
	v_add_f32_e32 v43, 1.0, v121
	v_mul_f32_e32 v76, v76, v40
	v_mul_f32_e32 v76, v184, v76
	v_add_f32_e32 v44, 1.0, v122
	v_mul_f32_e32 v77, v77, v40
	v_mul_f32_e32 v77, v185, v77
	v_add_f32_e32 v45, 1.0, v123
	v_fma_f32 v74, v42, v74, v104
	v_fma_f32 v75, v43, v75, v105
	v_fma_f32 v76, v44, v76, v106
	v_fma_f32 v77, v45, v77, v107
	v_cvt_pk_bf16_f32 v74, v74, v75
	v_cvt_pk_bf16_f32 v75, v76, v77
	global_store_dwordx2 v[62:63], v[74:75], off offset:512
	v_mul_f32_e32 v78, v78, v40
	v_mul_f32_e32 v78, v186, v78
	v_add_f32_e32 v42, 1.0, v124
	v_mul_f32_e32 v79, v79, v40
	v_mul_f32_e32 v79, v187, v79
	v_add_f32_e32 v43, 1.0, v125
	v_mul_f32_e32 v80, v80, v40
	v_mul_f32_e32 v80, v188, v80
	v_add_f32_e32 v44, 1.0, v126
	v_mul_f32_e32 v81, v81, v40
	v_mul_f32_e32 v81, v189, v81
	v_add_f32_e32 v45, 1.0, v127
	v_fma_f32 v78, v42, v78, v108
	v_fma_f32 v79, v43, v79, v109
	v_fma_f32 v80, v44, v80, v110
	v_fma_f32 v81, v45, v81, v111
	v_cvt_pk_bf16_f32 v78, v78, v79
	v_cvt_pk_bf16_f32 v79, v80, v81
	global_store_dwordx2 v[62:63], v[78:79], off offset:1024
	v_mul_f32_e32 v82, v82, v40
	v_mul_f32_e32 v82, v190, v82
	v_add_f32_e32 v42, 1.0, v128
	v_mul_f32_e32 v83, v83, v40
	v_mul_f32_e32 v83, v191, v83
	v_add_f32_e32 v43, 1.0, v129
	v_mul_f32_e32 v84, v84, v40
	v_mul_f32_e32 v84, v192, v84
	v_add_f32_e32 v44, 1.0, v130
	v_mul_f32_e32 v85, v85, v40
	v_mul_f32_e32 v85, v193, v85
	v_add_f32_e32 v45, 1.0, v131
	v_fma_f32 v82, v42, v82, v112
	v_fma_f32 v83, v43, v83, v113
	v_fma_f32 v84, v44, v84, v114
	v_fma_f32 v85, v45, v85, v115
	v_cvt_pk_bf16_f32 v82, v82, v83
	v_cvt_pk_bf16_f32 v83, v84, v85
	global_store_dwordx2 v[62:63], v[82:83], off offset:1536
	s_movk_i32 s60, 0x4200
.Lnm_adv1:
	s_cmpk_lt_u32 s60, 0x4200
	s_cbranch_scc1 .Lnm_it0
.Lnm_done:
.LBB0_931:
	s_or_b64 exec, exec, s[4:5]
	s_mov_b64 s[2:3], 0
.LBB0_932:
	s_andn2_b64 vcc, exec, s[2:3]
	s_cbranch_vccnz .LBB0_1070
	v_mov_b32_e32 v32, v164
	s_mov_b32 s14, s82
	s_cmpk_gt_i32 s14, 0x8f
	v_lshlrev_b32_e32 v36, 2, v32
	s_cbranch_scc1 .LBB0_943
	s_movk_i32 s2, 0xc00
	v_cmp_gt_i32_e64 s[40:41], s2, v32
	v_ashrrev_i32_e32 v0, 5, v32
	v_and_b32_e32 v37, 0x7c, v36
	s_movk_i32 s2, 0x600
	v_lshlrev_b32_e32 v24, 6, v0
	v_lshl_add_u32 v38, v0, 8, 0
	v_mul_lo_u32 v0, v0, s2
	s_waitcnt lgkmcnt(0)
	v_lshlrev_b32_e32 v1, 2, v37
	v_ashrrev_i32_e32 v26, 7, v32
	v_and_b32_e32 v40, 0x7f, v32
	v_add3_u32 v39, 0, v0, v1
	s_movk_i32 s2, 0x180
	v_lshl_add_u32 v0, v40, 2, 0
	v_lshlrev_b32_e32 v1, 9, v26
	v_ashrrev_i32_e32 v33, 31, v32
	v_ashrrev_i32_e32 v25, 31, v24
	v_cmp_gt_i32_e64 s[42:43], s2, v32
	v_ashrrev_i32_e32 v27, 31, v26
	v_add_u32_e32 v41, 0, v36
	v_lshlrev_b64 v[28:29], 2, v[32:33]
	v_add_u32_e32 v33, v0, v1
	s_mov_b32 s2, s14
	s_branch .LBB0_936
